# static s_setprio 1 for waves 0-3 (older half) only inside the two GEMM phases; no per-phase flips
# speedup vs baseline: 1.0044x; 1.0044x over previous
; #define PG8_STAGE(bufoff, gbase, voff) do { _Pragma("unroll") for (int _i = 0; _i < 2; ++_i) \
;         __builtin_amdgcn_global_load_lds((const unsigned*)((const char*)(gbase) + (voff)[_i]), (LAS unsigned*)(lds + (bufoff) + ldsw + _i * 8192), 16, 0, 0); } while (0)
; #define PG8_WAIT_V(n) asm volatile("s_waitcnt vmcnt(" #n ")" ::: "memory")
; #define PG8_BAR __builtin_amdgcn_s_barrier()
; template <bool REMAP>
; DI void gemm_phase(LAS unsigned char* lds, const u16* A, int lda, const u16* Bt, int K, u16* O, int ldc, int nunits) {
;     ...
;     const char* cA = (const char*)A + (size_t)cur.pm * tstepA; const char* cB = (const char*)Bt + (size_t)cur.pn * tstepB;
;     PG8_STAGE(PG8_SB(0, 0), cB, voffB); PG8_STAGE(PG8_SA(0, 0), cA + akb(0), voffA); PG8_STAGE(PG8_SB(0, 1), cB + hstepB, voffB); PG8_STAGE(PG8_SA(0, 1), cA + akb(0) + hstepA, voffA);
;     if (wr == 1) PG8_BAR;
;     PG8_WAIT_V(4); PG8_BAR;
;     PG8_STAGE(PG8_SB(1, 0), cB + kstep, voffB); PG8_STAGE(PG8_SA(1, 0), cA + akb(1), voffA); PG8_STAGE(PG8_SB(1, 1), cB + hstepB + kstep, voffB);
;     PG8_WAIT_V(6); PG8_BAR;
;     for (;;) {
;         const bool has_next = next_unit(ui + 1, nunits, nxt);
;         const char* nA = has_next ? (const char*)A + (size_t)nxt.pm * tstepA : cA; const char* nB = has_next ? (const char*)Bt + (size_t)nxt.pn * tstepB : cB;
.LBB0_136:
	s_ashr_i32 s5, s4, 31
	s_lshl_b64 s[12:13], s[4:5], 19
	s_add_u32 s12, s3, s12
	s_addc_u32 s13, s24, s13
	s_and_b64 s[14:15], s[22:23], exec
	s_cselect_b32 s5, s13, s11
	s_cselect_b32 s46, s12, s10
	s_ashr_i32 s7, s6, 31
	s_lshl_b64 s[14:15], s[6:7], 19
	s_add_u32 s14, s16, s14
	s_addc_u32 s15, s25, s15
	s_and_b64 s[22:23], s[22:23], exec
	s_cselect_b32 s7, s15, s21
	s_cselect_b32 s47, s14, s20
	s_add_u32 s49, s46, 0x80
	s_addc_u32 s50, s5, 0
	s_add_u32 s51, s20, 0x100
	s_addc_u32 s54, s21, 0
	s_add_u32 s22, s10, 0x40080
	s_addc_u32 s23, s11, 0
	s_mov_b32 s55, -2
	s_mov_b64 s[20:21], 0
	s_cmp_lt_u32 s27, 0x1000
	s_cbranch_scc0 .Lg1_noprio
	s_setprio 1

; template <bool REMAP>
; DI void gemm_phase(LAS unsigned char* lds, const u16* A, int lda, const u16* Bt, int K, u16* O, int ldc, int nunits) {
;     ...
;         const char* nA = has_next ? (const char*)A + (size_t)nxt.pm * tstepA : cA; const char* nB = has_next ? (const char*)Bt + (size_t)nxt.pn * tstepB : cB;
;     ...
;         if (!has_next) break;
; #pragma unroll
;         for (int a = 0; a < 2; ++a)
; #pragma unroll
;             for (int b = 0; b < 2; ++b)
; #pragma unroll
;                 for (int m = 0; m < 4; ++m)
; #pragma unroll
;                     for (int n = 0; n < 2; ++n) acc[a][b][m][n] = (f32x4){0.f, 0.f, 0.f, 0.f};
;         cur = nxt; cA = nA; cB = nB; ++ui;
.LBB0_386:
	s_ashr_i32 s5, s4, 31
	s_lshl_b64 s[12:13], s[4:5], 20
	s_add_u32 s12, s24, s12
	s_addc_u32 s13, s25, s13
	s_and_b64 s[14:15], s[14:15], exec
	s_cselect_b32 s5, s13, s21
	s_cselect_b32 s41, s12, s20
	s_add_u32 s14, s10, 0x80
	s_addc_u32 s15, s11, 0
	s_add_u32 s46, s20, 0x100
	v_mov_b32_e32 v2, 0
	s_addc_u32 s47, s21, 0
	s_mov_b32 s50, 0
	s_movk_i32 s49, 0xc0
	v_mov_b32_e32 v3, v2
	v_mov_b32_e32 v4, v2
	v_mov_b32_e32 v5, v2
	v_mov_b32_e32 v6, v2
	v_mov_b32_e32 v7, v2
	v_mov_b32_e32 v8, v2
	v_mov_b32_e32 v9, v2
	v_mov_b32_e32 v10, v2
	v_mov_b32_e32 v11, v2
	v_mov_b32_e32 v12, v2
	v_mov_b32_e32 v13, v2
	v_mov_b32_e32 v14, v2
	v_mov_b32_e32 v15, v2
	v_mov_b32_e32 v16, v2
	v_mov_b32_e32 v17, v2
	v_mov_b32_e32 v26, v2
	v_mov_b32_e32 v27, v2
	v_mov_b32_e32 v28, v2
	v_mov_b32_e32 v29, v2
	v_mov_b32_e32 v30, v2
	v_mov_b32_e32 v31, v2
	v_mov_b32_e32 v32, v2
	v_mov_b32_e32 v33, v2
	v_mov_b32_e32 v42, v2
	v_mov_b32_e32 v43, v2
	v_mov_b32_e32 v44, v2
	v_mov_b32_e32 v45, v2
	v_mov_b32_e32 v46, v2
	v_mov_b32_e32 v47, v2
	v_mov_b32_e32 v48, v2
	v_mov_b32_e32 v49, v2
	v_mov_b32_e32 v18, v2
	v_mov_b32_e32 v19, v2
	v_mov_b32_e32 v20, v2
	v_mov_b32_e32 v21, v2
	v_mov_b32_e32 v22, v2
	v_mov_b32_e32 v23, v2
	v_mov_b32_e32 v24, v2
	v_mov_b32_e32 v25, v2
	v_mov_b32_e32 v34, v2
	v_mov_b32_e32 v35, v2
	v_mov_b32_e32 v36, v2
	v_mov_b32_e32 v37, v2
	v_mov_b32_e32 v38, v2
	v_mov_b32_e32 v39, v2
	v_mov_b32_e32 v40, v2
	v_mov_b32_e32 v41, v2
	v_mov_b32_e32 v50, v2
	v_mov_b32_e32 v51, v2
	v_mov_b32_e32 v52, v2
	v_mov_b32_e32 v53, v2
	v_mov_b32_e32 v54, v2
	v_mov_b32_e32 v55, v2
	v_mov_b32_e32 v56, v2
	v_mov_b32_e32 v57, v2
	v_mov_b32_e32 v58, v2
	v_mov_b32_e32 v59, v2
	v_mov_b32_e32 v60, v2
	v_mov_b32_e32 v61, v2
	v_mov_b32_e32 v62, v2
	v_mov_b32_e32 v63, v2
	v_mov_b32_e32 v64, v2
	v_mov_b32_e32 v65, v2
	v_mov_b32_e32 v66, v2
	v_mov_b32_e32 v67, v2
	v_mov_b32_e32 v68, v2
	v_mov_b32_e32 v69, v2
	v_mov_b32_e32 v70, v2
	v_mov_b32_e32 v71, v2
	v_mov_b32_e32 v72, v2
	v_mov_b32_e32 v73, v2
	v_mov_b32_e32 v74, v2
	v_mov_b32_e32 v75, v2
	v_mov_b32_e32 v76, v2
	v_mov_b32_e32 v77, v2
	v_mov_b32_e32 v78, v2
	v_mov_b32_e32 v79, v2
	v_mov_b32_e32 v80, v2
	v_mov_b32_e32 v81, v2
	v_mov_b32_e32 v90, v2
	v_mov_b32_e32 v91, v2
	v_mov_b32_e32 v92, v2
	v_mov_b32_e32 v93, v2
	v_mov_b32_e32 v94, v2
	v_mov_b32_e32 v95, v2
	v_mov_b32_e32 v96, v2
	v_mov_b32_e32 v97, v2
	v_mov_b32_e32 v106, v2
	v_mov_b32_e32 v107, v2
	v_mov_b32_e32 v108, v2
	v_mov_b32_e32 v109, v2
	v_mov_b32_e32 v110, v2
	v_mov_b32_e32 v111, v2
	v_mov_b32_e32 v112, v2
	v_mov_b32_e32 v113, v2
	v_mov_b32_e32 v82, v2
	v_mov_b32_e32 v83, v2
	v_mov_b32_e32 v84, v2
	v_mov_b32_e32 v85, v2
	v_mov_b32_e32 v86, v2
	v_mov_b32_e32 v87, v2
	v_mov_b32_e32 v88, v2
	v_mov_b32_e32 v89, v2
	v_mov_b32_e32 v98, v2
	v_mov_b32_e32 v99, v2
	v_mov_b32_e32 v100, v2
	v_mov_b32_e32 v101, v2
	v_mov_b32_e32 v102, v2
	v_mov_b32_e32 v103, v2
	v_mov_b32_e32 v104, v2
	v_mov_b32_e32 v105, v2
	v_mov_b32_e32 v114, v2
	v_mov_b32_e32 v115, v2
	v_mov_b32_e32 v116, v2
	v_mov_b32_e32 v117, v2
	v_mov_b32_e32 v118, v2
	v_mov_b32_e32 v119, v2
	v_mov_b32_e32 v120, v2
	v_mov_b32_e32 v121, v2
	v_mov_b32_e32 v122, v2
	v_mov_b32_e32 v123, v2
	v_mov_b32_e32 v124, v2
	v_mov_b32_e32 v125, v2
	v_mov_b32_e32 v126, v2
	v_mov_b32_e32 v127, v2
	v_mov_b32_e32 v128, v2
	v_mov_b32_e32 v129, v2
	s_cmp_lt_u32 s27, 0x1000
	s_cbranch_scc0 .Lg2_noprio
	s_setprio 1
